# residual+LN epilogue last part: gamma/beta/shift/scale vectors of column groups 1-3 fetched together with group 0's (one wait); per-group load+vmcnt drains removed
# speedup vs baseline: 1.0038x; 1.0038x over previous
;   __device__ __forceinline__ void operator()(f32x4 (&acc)[2][2][4][2], int pm, int pn, int wr_, int wc_, int fr_, int fq_, bf16_t* shm, int tid) const {
;     ...
; #pragma unroll
;     for (int bj = 0; bj < 2; ++bj)
; #pragma unroll
;       for (int n = 0; n < 2; ++n) {
;         asm volatile("" ::: "memory");
;         const int col = pn * 256 + bj * 128 + wc * 32 + n * 16 + fq * 4;
;         const f32x4 gg = *(const f32x4*)(ng + col), bb = *(const f32x4*)(nb + col);
;         f32x4 sh = {0.f, 0.f, 0.f, 0.f}, sc = {0.f, 0.f, 0.f, 0.f};
;         if (!outp) { sh = *(const f32x4*)(msh + bio + col); sc = *(const f32x4*)(msc + bio + col); }
; #pragma unroll
;         for (int ai = 0; ai < 2; ++ai)
; #pragma unroll
;           for (int m = 0; m < 4; ++m) {
;             const int rl = ai * 128 + wr * 64 + m * 16 + fr, row = pm * 256 + rl;
;             const f2_t st = rst[rl];
;             f32x4 y = (acc[ai][bj][m][n] - st[0]) * st[1] * gg + bb;
.LBB0_232:
	s_or_b64 exec, exec, s[6:7]
	s_waitcnt lgkmcnt(0)
	s_barrier
	v_lshl_add_u64 v[158:159], s[88:89], 0, v[146:147]
	v_lshl_add_u64 v[160:161], s[66:67], 0, v[146:147]
	global_load_dwordx4 v[134:137], v[158:159], off
	global_load_dwordx4 v[138:141], v[160:161], off
	global_load_dwordx4 v[176:179], v[158:159], off offset:64
	global_load_dwordx4 v[180:183], v[160:161], off offset:64
	global_load_dwordx4 v[192:195], v[158:159], off offset:512
	global_load_dwordx4 v[196:199], v[160:161], off offset:512
	global_load_dwordx4 v[222:225], v[158:159], off offset:576
	global_load_dwordx4 v[228:231], v[160:161], off offset:576
	s_add_u32 s6, s77, s0
	s_addc_u32 s7, s90, s1
	s_add_u32 s0, s76, s0
	v_cndmask_b32_e64 v130, 0, 1, s[12:13]
	s_addc_u32 s1, s23, s1
	v_cmp_ne_u32_e64 s[10:11], 1, v130
	s_andn2_b64 vcc, exec, s[12:13]
	s_cbranch_vccz .LBB0_237
	v_mov_b32_e32 v162, 1.0
	v_mov_b32_e32 v130, 0
	v_mov_b32_e32 v131, v130
	v_mov_b32_e32 v132, v130
	v_mov_b32_e32 v133, v130
	v_mov_b32_e32 v163, v162
	v_mov_b32_e32 v164, v162
	v_mov_b32_e32 v165, v162
	s_branch .LBB0_238
.LBB0_237:
	v_lshl_add_u64 v[130:131], s[6:7], 0, v[146:147]
	global_load_dwordx4 v[142:145], v[130:131], off
	v_lshl_add_u64 v[130:131], s[0:1], 0, v[146:147]
	global_load_dwordx4 v[130:133], v[130:131], off
	v_lshl_add_u64 v[200:201], s[6:7], 0, v[146:147]
	global_load_dwordx4 v[184:187], v[200:201], off offset:64
	v_lshl_add_u64 v[248:249], s[0:1], 0, v[146:147]
	global_load_dwordx4 v[188:191], v[248:249], off offset:64
	global_load_dwordx4 v[214:217], v[200:201], off offset:512
	global_load_dwordx4 v[218:221], v[248:249], off offset:512
	global_load_dwordx4 v[232:235], v[200:201], off offset:576
	global_load_dwordx4 v[236:239], v[248:249], off offset:576
	s_waitcnt vmcnt(7)
	v_pk_add_f32 v[164:165], v[144:145], 1.0 op_sel_hi:[1,0]
	v_pk_add_f32 v[162:163], v[142:143], 1.0 op_sel_hi:[1,0]

; __device__ __forceinline__ unsigned pk2(float lo, float hi) { const f2_t v = {lo, hi}; return __builtin_bit_cast(unsigned, __builtin_convertvector(v, bf2_t)); }
;   __device__ __forceinline__ void operator()(f32x4 (&acc)[2][2][4][2], int pm, int pn, int wr_, int wc_, int fr_, int fq_, bf16_t* shm, int tid) const {
;     ...
;       for (int n = 0; n < 2; ++n) {
;         asm volatile("" ::: "memory");
;         const int col = pn * 256 + bj * 128 + wc * 32 + n * 16 + fq * 4;
;         const f32x4 gg = *(const f32x4*)(ng + col), bb = *(const f32x4*)(nb + col);
;         f32x4 sh = {0.f, 0.f, 0.f, 0.f}, sc = {0.f, 0.f, 0.f, 0.f};
;         if (!outp) { sh = *(const f32x4*)(msh + bio + col); sc = *(const f32x4*)(msc + bio + col); }
; #pragma unroll
;         for (int ai = 0; ai < 2; ++ai)
; #pragma unroll
;           for (int m = 0; m < 4; ++m) {
;             const int rl = ai * 128 + wr * 64 + m * 16 + fr, row = pm * 256 + rl;
;             const f2_t st = rst[rl];
;             f32x4 y = (acc[ai][bj][m][n] - st[0]) * st[1] * gg + bb;
;             if (outp) { *(f32x4*)(outp + (long)row * DM + col) = y; }
;             else {
;               y = y * (sc + 1.f) + sh;
;               u32x2 w; w.x = pk2(y[0], y[1]); w.y = pk2(y[2], y[3]);
;               *(u32x2*)(H + (long)row * DM + col) = w;
.LBB0_270:
	v_mov_b32_e32 v6, v176
	v_mov_b32_e32 v7, v177
	v_mov_b32_e32 v8, v178
	v_mov_b32_e32 v9, v179
	v_mov_b32_e32 v10, v180
	v_mov_b32_e32 v11, v181
	v_mov_b32_e32 v12, v182
	v_mov_b32_e32 v13, v183
	s_and_b64 vcc, exec, s[10:11]
	s_cbranch_vccz .LBB0_272
	v_mov_b32_e32 v24, 1.0
	v_mov_b32_e32 v2, 0
	v_mov_b32_e32 v3, v2
	v_mov_b32_e32 v4, v2
	v_mov_b32_e32 v5, v2
	v_mov_b32_e32 v25, v24
	v_mov_b32_e32 v26, v24
	v_mov_b32_e32 v27, v24
	s_branch .LBB0_273
.LBB0_272:
	v_lshl_add_u64 v[2:3], s[6:7], 0, v[146:147]
	v_mov_b32_e32 v14, v184
	v_mov_b32_e32 v15, v185
	v_mov_b32_e32 v16, v186
	v_mov_b32_e32 v17, v187
	v_lshl_add_u64 v[2:3], s[0:1], 0, v[146:147]
	v_mov_b32_e32 v2, v188
	v_mov_b32_e32 v3, v189
	v_mov_b32_e32 v4, v190
	v_mov_b32_e32 v5, v191
	v_pk_add_f32 v[26:27], v[16:17], 1.0 op_sel_hi:[1,0]
	v_pk_add_f32 v[24:25], v[14:15], 1.0 op_sel_hi:[1,0]
.LBB0_273:
	ds_read_b64 v[14:15], v166
	s_and_b64 vcc, exec, s[8:9]
	s_mov_b64 s[14:15], -1
	s_waitcnt lgkmcnt(0)
	v_sub_f32_e32 v17, v33, v14
	v_sub_f32_e32 v16, v32, v14
	v_sub_f32_e32 v29, v31, v14
	v_sub_f32_e32 v28, v30, v14
	v_pk_mul_f32 v[28:29], v[14:15], v[28:29] op_sel:[1,0]
	v_pk_mul_f32 v[14:15], v[14:15], v[16:17] op_sel:[1,0]
	v_pk_fma_f32 v[16:17], v[8:9], v[14:15], v[12:13]
	v_pk_fma_f32 v[14:15], v[6:7], v[28:29], v[10:11]
	s_cbranch_vccnz .LBB0_275
	v_lshlrev_b64 v[28:29], 12, v[148:149]
	v_lshl_add_u64 v[28:29], v[142:143], 0, v[28:29]
	s_mov_b64 s[14:15], 0
	global_store_dwordx4 v[28:29], v[14:17], off offset:64

; __device__ __forceinline__ unsigned pk2(float lo, float hi) { const f2_t v = {lo, hi}; return __builtin_bit_cast(unsigned, __builtin_convertvector(v, bf2_t)); }
;   __device__ __forceinline__ void operator()(f32x4 (&acc)[2][2][4][2], int pm, int pn, int wr_, int wc_, int fr_, int fq_, bf16_t* shm, int tid) const {
;     ...
;       for (int n = 0; n < 2; ++n) {
;         asm volatile("" ::: "memory");
;         const int col = pn * 256 + bj * 128 + wc * 32 + n * 16 + fq * 4;
;         const f32x4 gg = *(const f32x4*)(ng + col), bb = *(const f32x4*)(nb + col);
;         f32x4 sh = {0.f, 0.f, 0.f, 0.f}, sc = {0.f, 0.f, 0.f, 0.f};
;         if (!outp) { sh = *(const f32x4*)(msh + bio + col); sc = *(const f32x4*)(msc + bio + col); }
; #pragma unroll
;         for (int ai = 0; ai < 2; ++ai)
; #pragma unroll
;           for (int m = 0; m < 4; ++m) {
;             const int rl = ai * 128 + wr * 64 + m * 16 + fr, row = pm * 256 + rl;
;             const f2_t st = rst[rl];
;             f32x4 y = (acc[ai][bj][m][n] - st[0]) * st[1] * gg + bb;
;             if (outp) { *(f32x4*)(outp + (long)row * DM + col) = y; }
;             else {
;               y = y * (sc + 1.f) + sh;
;               u32x2 w; w.x = pk2(y[0], y[1]); w.y = pk2(y[2], y[3]);
;               *(u32x2*)(H + (long)row * DM + col) = w;
.LBB0_305:
	v_mov_b32_e32 v6, v192
	v_mov_b32_e32 v7, v193
	v_mov_b32_e32 v8, v194
	v_mov_b32_e32 v9, v195
	v_mov_b32_e32 v10, v196
	v_mov_b32_e32 v11, v197
	v_mov_b32_e32 v12, v198
	v_mov_b32_e32 v13, v199
	s_and_b64 vcc, exec, s[10:11]
	s_cbranch_vccz .LBB0_307
	v_mov_b32_e32 v24, 1.0
	v_mov_b32_e32 v2, 0
	v_mov_b32_e32 v3, v2
	v_mov_b32_e32 v4, v2
	v_mov_b32_e32 v5, v2
	v_mov_b32_e32 v25, v24
	v_mov_b32_e32 v26, v24
	v_mov_b32_e32 v27, v24
	s_branch .LBB0_308
.LBB0_307:
	v_lshl_add_u64 v[2:3], s[6:7], 0, v[146:147]
	v_mov_b32_e32 v14, v214
	v_mov_b32_e32 v15, v215
	v_mov_b32_e32 v16, v216
	v_mov_b32_e32 v17, v217
	v_lshl_add_u64 v[2:3], s[0:1], 0, v[146:147]
	v_mov_b32_e32 v2, v218
	v_mov_b32_e32 v3, v219
	v_mov_b32_e32 v4, v220
	v_mov_b32_e32 v5, v221
	v_pk_add_f32 v[26:27], v[16:17], 1.0 op_sel_hi:[1,0]
	v_pk_add_f32 v[24:25], v[14:15], 1.0 op_sel_hi:[1,0]
.LBB0_308:
	ds_read_b64 v[14:15], v166
	s_and_b64 vcc, exec, s[8:9]
	s_mov_b64 s[14:15], -1
	s_waitcnt lgkmcnt(0)
	v_sub_f32_e32 v17, v65, v14
	v_sub_f32_e32 v16, v64, v14
	v_sub_f32_e32 v29, v63, v14
	v_sub_f32_e32 v28, v62, v14
	v_pk_mul_f32 v[28:29], v[14:15], v[28:29] op_sel:[1,0]
	v_pk_mul_f32 v[14:15], v[14:15], v[16:17] op_sel:[1,0]
	v_pk_fma_f32 v[16:17], v[8:9], v[14:15], v[12:13]
	v_pk_fma_f32 v[14:15], v[6:7], v[28:29], v[10:11]
	s_cbranch_vccnz .LBB0_310
	v_lshlrev_b64 v[28:29], 12, v[148:149]
	v_lshl_add_u64 v[28:29], v[142:143], 0, v[28:29]
	s_mov_b64 s[14:15], 0
	global_store_dwordx4 v[28:29], v[14:17], off offset:512

; __device__ __forceinline__ unsigned pk2(float lo, float hi) { const f2_t v = {lo, hi}; return __builtin_bit_cast(unsigned, __builtin_convertvector(v, bf2_t)); }
;   __device__ __forceinline__ void operator()(f32x4 (&acc)[2][2][4][2], int pm, int pn, int wr_, int wc_, int fr_, int fq_, bf16_t* shm, int tid) const {
;     ...
;       for (int n = 0; n < 2; ++n) {
;         asm volatile("" ::: "memory");
;         const int col = pn * 256 + bj * 128 + wc * 32 + n * 16 + fq * 4;
;         const f32x4 gg = *(const f32x4*)(ng + col), bb = *(const f32x4*)(nb + col);
;         f32x4 sh = {0.f, 0.f, 0.f, 0.f}, sc = {0.f, 0.f, 0.f, 0.f};
;         if (!outp) { sh = *(const f32x4*)(msh + bio + col); sc = *(const f32x4*)(msc + bio + col); }
; #pragma unroll
;         for (int ai = 0; ai < 2; ++ai)
; #pragma unroll
;           for (int m = 0; m < 4; ++m) {
;             const int rl = ai * 128 + wr * 64 + m * 16 + fr, row = pm * 256 + rl;
;             const f2_t st = rst[rl];
;             f32x4 y = (acc[ai][bj][m][n] - st[0]) * st[1] * gg + bb;
;             if (outp) { *(f32x4*)(outp + (long)row * DM + col) = y; }
;             else {
;               y = y * (sc + 1.f) + sh;
;               u32x2 w; w.x = pk2(y[0], y[1]); w.y = pk2(y[2], y[3]);
;               *(u32x2*)(H + (long)row * DM + col) = w;
.LBB0_340:
	v_mov_b32_e32 v6, v222
	v_mov_b32_e32 v7, v223
	v_mov_b32_e32 v8, v224
	v_mov_b32_e32 v9, v225
	v_mov_b32_e32 v10, v228
	v_mov_b32_e32 v11, v229
	v_mov_b32_e32 v12, v230
	v_mov_b32_e32 v13, v231
	s_and_b64 vcc, exec, s[10:11]
	s_cbranch_vccz .LBB0_342
	v_mov_b32_e32 v24, 1.0
	v_mov_b32_e32 v2, 0
	v_mov_b32_e32 v3, v2
	v_mov_b32_e32 v4, v2
	v_mov_b32_e32 v5, v2
	v_mov_b32_e32 v25, v24
	v_mov_b32_e32 v26, v24
	v_mov_b32_e32 v27, v24
	s_branch .LBB0_343
.LBB0_342:
	v_lshl_add_u64 v[2:3], s[6:7], 0, v[146:147]
	v_mov_b32_e32 v14, v232
	v_mov_b32_e32 v15, v233
	v_mov_b32_e32 v16, v234
	v_mov_b32_e32 v17, v235
	v_lshl_add_u64 v[2:3], s[0:1], 0, v[146:147]
	v_mov_b32_e32 v2, v236
	v_mov_b32_e32 v3, v237
	v_mov_b32_e32 v4, v238
	v_mov_b32_e32 v5, v239
	v_pk_add_f32 v[26:27], v[16:17], 1.0 op_sel_hi:[1,0]
	v_pk_add_f32 v[24:25], v[14:15], 1.0 op_sel_hi:[1,0]
.LBB0_343:
	ds_read_b64 v[14:15], v166
	s_and_b64 vcc, exec, s[8:9]
	s_mov_b64 s[0:1], -1
	s_waitcnt lgkmcnt(0)
	v_sub_f32_e32 v17, v101, v14
	v_sub_f32_e32 v16, v100, v14
	v_sub_f32_e32 v29, v99, v14
	v_sub_f32_e32 v28, v98, v14
	v_pk_mul_f32 v[28:29], v[14:15], v[28:29] op_sel:[1,0]
	v_pk_mul_f32 v[14:15], v[14:15], v[16:17] op_sel:[1,0]
	v_pk_fma_f32 v[16:17], v[8:9], v[14:15], v[12:13]
	v_pk_fma_f32 v[14:15], v[6:7], v[28:29], v[10:11]
	s_cbranch_vccnz .LBB0_345
	v_lshlrev_b64 v[28:29], 12, v[148:149]
	v_lshl_add_u64 v[28:29], v[142:143], 0, v[28:29]
	s_mov_b64 s[0:1], 0
	global_store_dwordx4 v[28:29], v[14:17], off offset:576

; __device__ __forceinline__ unsigned pk2(float lo, float hi) { const f2_t v = {lo, hi}; return __builtin_bit_cast(unsigned, __builtin_convertvector(v, bf2_t)); }
;   __device__ __forceinline__ void operator()(f32x4 (&acc)[2][2][4][2], int pm, int pn, int wr_, int wc_, int fr_, int fq_, bf16_t* shm, int tid) const {
;     ...
; #pragma unroll
;     for (int bj = 0; bj < 2; ++bj)
; #pragma unroll
;       for (int n = 0; n < 2; ++n) {
;         asm volatile("" ::: "memory");
;         const int col = pn * 256 + bj * 128 + wc * 32 + n * 16 + fq * 4;
;         const f32x4 gg = *(const f32x4*)(ng + col), bb = *(const f32x4*)(nb + col);
;         f32x4 sh = {0.f, 0.f, 0.f, 0.f}, sc = {0.f, 0.f, 0.f, 0.f};
;         if (!outp) { sh = *(const f32x4*)(msh + bio + col); sc = *(const f32x4*)(msc + bio + col); }
; #pragma unroll
;         for (int ai = 0; ai < 2; ++ai)
; #pragma unroll
;           for (int m = 0; m < 4; ++m) {
;             const int rl = ai * 128 + wr * 64 + m * 16 + fr, row = pm * 256 + rl;
;             const f2_t st = rst[rl];
;             f32x4 y = (acc[ai][bj][m][n] - st[0]) * st[1] * gg + bb;
;             if (outp) { *(f32x4*)(outp + (long)row * DM + col) = y; }
;             else {
;               y = y * (sc + 1.f) + sh;
;               u32x2 w; w.x = pk2(y[0], y[1]); w.y = pk2(y[2], y[3]);
;               *(u32x2*)(H + (long)row * DM + col) = w;
;               if (HA && (rl == 0 || rl == 255)) *(u32x2*)(HA + (long)(pm * 2 + (rl == 255)) * DM + col) = w;
.LBB0_579:
	s_or_b64 exec, exec, s[0:1]
	s_add_u32 s0, s29, s6
	s_addc_u32 s1, s30, s7
	s_add_u32 s6, s24, s6
	s_addc_u32 s7, s28, s7
	s_waitcnt lgkmcnt(0)
	s_barrier
	v_lshl_add_u64 v[144:145], s[78:79], 0, v[146:147]
	v_lshl_add_u64 v[148:149], s[42:43], 0, v[146:147]
	v_lshl_add_u64 v[150:151], s[0:1], 0, v[146:147]
	v_lshl_add_u64 v[146:147], s[6:7], 0, v[146:147]
	global_load_dwordx4 v[130:133], v[144:145], off
	global_load_dwordx4 v[134:137], v[148:149], off
	global_load_dwordx4 v[138:141], v[146:147], off
	global_load_dwordx4 v[154:157], v[150:151], off
	global_load_dwordx4 v[176:179], v[150:151], off offset:64
	global_load_dwordx4 v[180:183], v[144:145], off offset:64
	global_load_dwordx4 v[184:187], v[148:149], off offset:64
	global_load_dwordx4 v[188:191], v[146:147], off offset:64
	global_load_dwordx4 v[192:195], v[150:151], off offset:512
	global_load_dwordx4 v[196:199], v[144:145], off offset:512
	global_load_dwordx4 v[200:203], v[148:149], off offset:512
	global_load_dwordx4 v[204:207], v[146:147], off offset:512
	global_load_dwordx4 v[208:211], v[150:151], off offset:576
	global_load_dwordx4 v[212:215], v[144:145], off offset:576
	global_load_dwordx4 v[216:219], v[148:149], off offset:576
	global_load_dwordx4 v[228:231], v[146:147], off offset:576
	v_readlane_b32 s44, v252, 20
	v_lshlrev_b32_e32 v0, 1, v0
	v_readlane_b32 s50, v252, 26
	v_readlane_b32 s51, v252, 27
	v_readlane_b32 s54, v252, 30
	v_readlane_b32 s55, v252, 31
	v_add_u32_e32 v158, s82, v160
	v_ashrrev_i32_e32 v159, 31, v158
	v_lshl_add_u64 v[142:143], s[54:55], 0, v[0:1]
	v_readlane_b32 s0, v251, 7
	v_cmp_eq_u32_e32 vcc, 0, v160
	v_readlane_b32 s1, v251, 8
	s_lshl_b32 s4, s4, 1
	s_and_b64 s[6:7], s[0:1], vcc
	v_readlane_b32 s45, v252, 21
	v_readlane_b32 s46, v252, 22
	v_readlane_b32 s47, v252, 23
	v_readlane_b32 s48, v252, 24
	v_readlane_b32 s49, v252, 25
	v_readlane_b32 s52, v252, 28
	v_readlane_b32 s53, v252, 29
	v_readlane_b32 s56, v252, 32
	v_readlane_b32 s57, v252, 33
	v_readlane_b32 s58, v252, 34
	v_readlane_b32 s59, v252, 35
	s_waitcnt vmcnt(0)
	v_pk_add_f32 v[152:153], v[156:157], 1.0 op_sel_hi:[1,0]
	v_lshl_add_u64 v[156:157], s[50:51], 0, v[0:1]
	v_lshl_add_u32 v0, v160, 3, 16
	v_add_u32_e32 v0, 0x22000, v0
	ds_read_b64 v[162:163], v0
	v_pk_add_f32 v[154:155], v[154:155], 1.0 op_sel_hi:[1,0]
	s_waitcnt lgkmcnt(0)
	v_sub_f32_e32 v127, v127, v162
	v_sub_f32_e32 v126, v126, v162
	v_sub_f32_e32 v129, v129, v162
	v_sub_f32_e32 v128, v128, v162
	v_pk_mul_f32 v[126:127], v[162:163], v[126:127] op_sel:[1,0]
	v_pk_mul_f32 v[128:129], v[162:163], v[128:129] op_sel:[1,0]
	v_pk_fma_f32 v[126:127], v[130:131], v[126:127], v[134:135]
	v_pk_fma_f32 v[128:129], v[132:133], v[128:129], v[136:137]
	v_pk_fma_f32 v[126:127], v[154:155], v[126:127], v[138:139]
	v_pk_fma_f32 v[162:163], v[152:153], v[128:129], v[140:141]
	v_cvt_pk_bf16_f32 v128, v126, v127
	v_lshlrev_b64 v[126:127], 11, v[158:159]
	v_cvt_pk_bf16_f32 v129, v162, v163
	v_lshl_add_u64 v[126:127], v[156:157], 0, v[126:127]
	global_store_dwordx2 v[126:127], v[128:129], off
	s_and_saveexec_b64 s[0:1], s[6:7]
	s_cbranch_execz .LBB0_581
	s_ashr_i32 s5, s4, 31
	s_lshl_b64 s[8:9], s[4:5], 11
	v_lshl_add_u64 v[162:163], v[142:143], 0, s[8:9]
	global_store_dwordx2 v[162:163], v[128:129], off

; __device__ __forceinline__ unsigned pk2(float lo, float hi) { const f2_t v = {lo, hi}; return __builtin_bit_cast(unsigned, __builtin_convertvector(v, bf2_t)); }
;   __device__ __forceinline__ void operator()(f32x4 (&acc)[2][2][4][2], int pm, int pn, int wr_, int wc_, int fr_, int fq_, bf16_t* shm, int tid) const {
;     ...
;       for (int n = 0; n < 2; ++n) {
;         asm volatile("" ::: "memory");
;         const int col = pn * 256 + bj * 128 + wc * 32 + n * 16 + fq * 4;
;         const f32x4 gg = *(const f32x4*)(ng + col), bb = *(const f32x4*)(nb + col);
;         f32x4 sh = {0.f, 0.f, 0.f, 0.f}, sc = {0.f, 0.f, 0.f, 0.f};
;         if (!outp) { sh = *(const f32x4*)(msh + bio + col); sc = *(const f32x4*)(msc + bio + col); }
; #pragma unroll
;         for (int ai = 0; ai < 2; ++ai)
; #pragma unroll
;           for (int m = 0; m < 4; ++m) {
;             const int rl = ai * 128 + wr * 64 + m * 16 + fr, row = pm * 256 + rl;
;             const f2_t st = rst[rl];
;             f32x4 y = (acc[ai][bj][m][n] - st[0]) * st[1] * gg + bb;
;             if (outp) { *(f32x4*)(outp + (long)row * DM + col) = y; }
;             else {
;               y = y * (sc + 1.f) + sh;
;               u32x2 w; w.x = pk2(y[0], y[1]); w.y = pk2(y[2], y[3]);
;               *(u32x2*)(H + (long)row * DM + col) = w;
;               if (HA && (rl == 0 || rl == 255)) *(u32x2*)(HA + (long)(pm * 2 + (rl == 255)) * DM + col) = w;
.LBB0_587:
	s_or_b64 exec, exec, s[0:1]
	v_mov_b32_e32 v130, v176
	v_mov_b32_e32 v131, v177
	v_mov_b32_e32 v132, v178
	v_mov_b32_e32 v133, v179
	v_mov_b32_e32 v2, v180
	v_mov_b32_e32 v3, v181
	v_mov_b32_e32 v4, v182
	v_mov_b32_e32 v5, v183
	v_mov_b32_e32 v14, v184
	v_mov_b32_e32 v15, v185
	v_mov_b32_e32 v16, v186
	v_mov_b32_e32 v17, v187
	v_mov_b32_e32 v6, v188
	v_mov_b32_e32 v7, v189
	v_mov_b32_e32 v8, v190
	v_mov_b32_e32 v9, v191
	ds_read_b64 v[54:55], v0
	s_waitcnt lgkmcnt(0)
	v_sub_f32_e32 v57, v83, v54
	v_sub_f32_e32 v56, v82, v54
	v_sub_f32_e32 v83, v85, v54
	v_sub_f32_e32 v82, v84, v54
	v_pk_mul_f32 v[82:83], v[54:55], v[82:83] op_sel:[1,0]
	v_pk_mul_f32 v[84:85], v[54:55], v[56:57] op_sel:[1,0]
	v_pk_add_f32 v[54:55], v[132:133], 1.0 op_sel_hi:[1,0]
	v_pk_add_f32 v[56:57], v[130:131], 1.0 op_sel_hi:[1,0]
	v_pk_fma_f32 v[84:85], v[2:3], v[84:85], v[14:15]
	v_pk_fma_f32 v[82:83], v[4:5], v[82:83], v[16:17]
	v_pk_fma_f32 v[130:131], v[54:55], v[82:83], v[8:9]
	v_pk_fma_f32 v[82:83], v[56:57], v[84:85], v[6:7]
	s_nop 0
	v_cvt_pk_bf16_f32 v82, v82, v83
	v_cvt_pk_bf16_f32 v83, v130, v131
	global_store_dwordx2 v[126:127], v[82:83], off offset:32
	s_and_saveexec_b64 s[0:1], s[6:7]
	s_cbranch_execz .LBB0_589
	s_ashr_i32 s5, s4, 31
	s_lshl_b64 s[12:13], s[4:5], 11
	v_lshl_add_u64 v[84:85], v[142:143], 0, s[12:13]
	global_store_dwordx2 v[84:85], v[82:83], off offset:32

; __device__ __forceinline__ unsigned pk2(float lo, float hi) { const f2_t v = {lo, hi}; return __builtin_bit_cast(unsigned, __builtin_convertvector(v, bf2_t)); }
;   __device__ __forceinline__ void operator()(f32x4 (&acc)[2][2][4][2], int pm, int pn, int wr_, int wc_, int fr_, int fq_, bf16_t* shm, int tid) const {
;     ...
;       for (int n = 0; n < 2; ++n) {
;         asm volatile("" ::: "memory");
;         const int col = pn * 256 + bj * 128 + wc * 32 + n * 16 + fq * 4;
;         const f32x4 gg = *(const f32x4*)(ng + col), bb = *(const f32x4*)(nb + col);
;         f32x4 sh = {0.f, 0.f, 0.f, 0.f}, sc = {0.f, 0.f, 0.f, 0.f};
;         if (!outp) { sh = *(const f32x4*)(msh + bio + col); sc = *(const f32x4*)(msc + bio + col); }
; #pragma unroll
;         for (int ai = 0; ai < 2; ++ai)
; #pragma unroll
;           for (int m = 0; m < 4; ++m) {
;             const int rl = ai * 128 + wr * 64 + m * 16 + fr, row = pm * 256 + rl;
;             const f2_t st = rst[rl];
;             f32x4 y = (acc[ai][bj][m][n] - st[0]) * st[1] * gg + bb;
;             if (outp) { *(f32x4*)(outp + (long)row * DM + col) = y; }
;             else {
;               y = y * (sc + 1.f) + sh;
;               u32x2 w; w.x = pk2(y[0], y[1]); w.y = pk2(y[2], y[3]);
;               *(u32x2*)(H + (long)row * DM + col) = w;
;               if (HA && (rl == 0 || rl == 255)) *(u32x2*)(HA + (long)(pm * 2 + (rl == 255)) * DM + col) = w;
.LBB0_595:
	s_or_b64 exec, exec, s[0:1]
	v_mov_b32_e32 v16, v192
	v_mov_b32_e32 v17, v193
	v_mov_b32_e32 v18, v194
	v_mov_b32_e32 v19, v195
	v_mov_b32_e32 v2, v196
	v_mov_b32_e32 v3, v197
	v_mov_b32_e32 v4, v198
	v_mov_b32_e32 v5, v199
	v_mov_b32_e32 v10, v200
	v_mov_b32_e32 v11, v201
	v_mov_b32_e32 v12, v202
	v_mov_b32_e32 v13, v203
	v_mov_b32_e32 v6, v204
	v_mov_b32_e32 v7, v205
	v_mov_b32_e32 v8, v206
	v_mov_b32_e32 v9, v207
	ds_read_b64 v[14:15], v0
	s_waitcnt lgkmcnt(0)
	v_sub_f32_e32 v21, v99, v14
	v_sub_f32_e32 v20, v98, v14
	v_sub_f32_e32 v27, v101, v14
	v_sub_f32_e32 v26, v100, v14
	v_pk_mul_f32 v[26:27], v[14:15], v[26:27] op_sel:[1,0]
	v_pk_mul_f32 v[20:21], v[14:15], v[20:21] op_sel:[1,0]
	v_pk_add_f32 v[14:15], v[18:19], 1.0 op_sel_hi:[1,0]
	v_pk_add_f32 v[16:17], v[16:17], 1.0 op_sel_hi:[1,0]
	v_pk_fma_f32 v[18:19], v[2:3], v[20:21], v[10:11]
	v_pk_fma_f32 v[20:21], v[4:5], v[26:27], v[12:13]
	v_pk_fma_f32 v[18:19], v[16:17], v[18:19], v[6:7]
	v_pk_fma_f32 v[20:21], v[14:15], v[20:21], v[8:9]
	v_cvt_pk_bf16_f32 v18, v18, v19
	v_cvt_pk_bf16_f32 v19, v20, v21
	global_store_dwordx2 v[126:127], v[18:19], off offset:256
	s_and_saveexec_b64 s[0:1], s[6:7]
	s_cbranch_execz .LBB0_597
	s_ashr_i32 s5, s4, 31
	s_lshl_b64 s[12:13], s[4:5], 11
	v_lshl_add_u64 v[20:21], v[142:143], 0, s[12:13]
	global_store_dwordx2 v[20:21], v[18:19], off offset:256

; __device__ __forceinline__ unsigned pk2(float lo, float hi) { const f2_t v = {lo, hi}; return __builtin_bit_cast(unsigned, __builtin_convertvector(v, bf2_t)); }
;   __device__ __forceinline__ void operator()(f32x4 (&acc)[2][2][4][2], int pm, int pn, int wr_, int wc_, int fr_, int fq_, bf16_t* shm, int tid) const {
;     ...
;       for (int n = 0; n < 2; ++n) {
;         asm volatile("" ::: "memory");
;         const int col = pn * 256 + bj * 128 + wc * 32 + n * 16 + fq * 4;
;         const f32x4 gg = *(const f32x4*)(ng + col), bb = *(const f32x4*)(nb + col);
;         f32x4 sh = {0.f, 0.f, 0.f, 0.f}, sc = {0.f, 0.f, 0.f, 0.f};
;         if (!outp) { sh = *(const f32x4*)(msh + bio + col); sc = *(const f32x4*)(msc + bio + col); }
; #pragma unroll
;         for (int ai = 0; ai < 2; ++ai)
; #pragma unroll
;           for (int m = 0; m < 4; ++m) {
;             const int rl = ai * 128 + wr * 64 + m * 16 + fr, row = pm * 256 + rl;
;             const f2_t st = rst[rl];
;             f32x4 y = (acc[ai][bj][m][n] - st[0]) * st[1] * gg + bb;
;             if (outp) { *(f32x4*)(outp + (long)row * DM + col) = y; }
;             else {
;               y = y * (sc + 1.f) + sh;
;               u32x2 w; w.x = pk2(y[0], y[1]); w.y = pk2(y[2], y[3]);
;               *(u32x2*)(H + (long)row * DM + col) = w;
;               if (HA && (rl == 0 || rl == 255)) *(u32x2*)(HA + (long)(pm * 2 + (rl == 255)) * DM + col) = w;
.LBB0_603:
	s_or_b64 exec, exec, s[0:1]
	v_mov_b32_e32 v16, v208
	v_mov_b32_e32 v17, v209
	v_mov_b32_e32 v18, v210
	v_mov_b32_e32 v19, v211
	v_mov_b32_e32 v2, v212
	v_mov_b32_e32 v3, v213
	v_mov_b32_e32 v4, v214
	v_mov_b32_e32 v5, v215
	v_mov_b32_e32 v10, v216
	v_mov_b32_e32 v11, v217
	v_mov_b32_e32 v12, v218
	v_mov_b32_e32 v13, v219
	v_mov_b32_e32 v6, v228
	v_mov_b32_e32 v7, v229
	v_mov_b32_e32 v8, v230
	v_mov_b32_e32 v9, v231
	ds_read_b64 v[14:15], v0
	s_waitcnt lgkmcnt(0)
	v_sub_f32_e32 v21, v115, v14
	v_sub_f32_e32 v20, v114, v14
	v_sub_f32_e32 v23, v117, v14
	v_sub_f32_e32 v22, v116, v14
	v_pk_mul_f32 v[22:23], v[14:15], v[22:23] op_sel:[1,0]
	v_pk_mul_f32 v[20:21], v[14:15], v[20:21] op_sel:[1,0]
	v_pk_add_f32 v[14:15], v[18:19], 1.0 op_sel_hi:[1,0]
	v_pk_add_f32 v[16:17], v[16:17], 1.0 op_sel_hi:[1,0]
	v_pk_fma_f32 v[18:19], v[2:3], v[20:21], v[10:11]
	v_pk_fma_f32 v[20:21], v[4:5], v[22:23], v[12:13]
	v_pk_fma_f32 v[18:19], v[16:17], v[18:19], v[6:7]
	v_pk_fma_f32 v[20:21], v[14:15], v[20:21], v[8:9]
	v_cvt_pk_bf16_f32 v18, v18, v19
	v_cvt_pk_bf16_f32 v19, v20, v21
	global_store_dwordx2 v[126:127], v[18:19], off offset:288
	s_and_saveexec_b64 s[0:1], s[6:7]
	s_cbranch_execz .LBB0_605
	s_ashr_i32 s5, s4, 31
	s_lshl_b64 s[6:7], s[4:5], 11
	v_lshl_add_u64 v[20:21], v[142:143], 0, s[6:7]
	global_store_dwordx2 v[20:21], v[18:19], off offset:288
